# K/V^T buffers relocated to slot 7; seam 9 XCD-local as well
# speedup vs baseline: 1.0651x; 1.0033x over previous
.LBB0_1483:
	v_readlane_b32 s16, v244, 0
	v_readlane_b32 s17, v244, 1
	v_readlane_b32 s18, v244, 2
	v_readlane_b32 s19, v244, 3
	v_readlane_b32 s20, v244, 4
	v_readlane_b32 s21, v244, 5
	v_readlane_b32 s22, v244, 6
	v_readlane_b32 s23, v244, 7
	s_mov_b64 s[16:17], s[20:21]
	s_mov_b64 s[18:19], s[22:23]
	s_add_u32 s6, s18, 0x15000000
	s_addc_u32 s7, s19, 0
	s_lshl_b32 s8, s8, 5
	s_and_b32 s16, s8, 0x60
	s_mov_b64 s[8:9], 0x80
	s_add_i32 m0, s47, 0x18000
	v_lshl_add_u64 v[6:7], v[6:7], 0, s[8:9]
	s_lshl_b32 s13, s12, 13
	s_waitcnt vmcnt(2)
	s_barrier
	global_load_lds_dwordx4 v[6:7], off
	v_lshl_add_u64 v[2:3], v[2:3], 0, s[8:9]
	s_add_i32 m0, s47, 0x1a000
	s_add_i32 s51, s47, 0x8000
	s_add_i32 s52, s47, 0xa000
	global_load_lds_dwordx4 v[2:3], off
	v_lshl_add_u64 v[0:1], v[0:1], 0, s[8:9]
	s_mov_b32 m0, s51
	s_add_u32 s14, s34, 0x40080
	global_load_lds_dwordx4 v[0:1], off
	v_lshl_add_u64 v[0:1], v[4:5], 0, s[8:9]
	s_mov_b32 m0, s52
	s_addc_u32 s15, s35, 0
	global_load_lds_dwordx4 v[0:1], off
	s_add_i32 m0, s47, 0x1c000
	v_lshl_add_u64 v[0:1], s[14:15], 0, v[130:131]
	global_load_lds_dwordx4 v[0:1], off
	v_lshl_add_u64 v[0:1], s[14:15], 0, v[134:135]
	s_add_i32 m0, s47, 0x1e000
	v_lshlrev_b32_e32 v2, 8, v182
	global_load_lds_dwordx4 v[0:1], off
	v_and_b32_e32 v2, 0x38000, v2
	v_lshlrev_b32_e32 v3, 11, v143
	v_or3_b32 v2, v142, v2, v3
	v_lshlrev_b32_e32 v1, 2, v149
	v_add_u32_e32 v138, v2, v146
	v_lshlrev_b32_e32 v2, 4, v147
	v_lshl_or_b32 v0, v149, 6, v150
	v_and_b32_e32 v1, 32, v1
	s_waitcnt vmcnt(6)
	s_cmpk_lt_u32 s11, 0x100
	v_and_b32_e32 v2, 0x78000, v2
	s_sext_i32_i8 s29, s10
	v_bitop3_b32 v1, v0, s13, v1 bitop3:0xde
	v_lshl_or_b32 v153, s16, 7, v151
	s_cselect_b64 s[10:11], -1, 0
	v_or_b32_e32 v0, s16, v148
	v_or3_b32 v2, v142, v2, v3
	s_add_i32 s55, 0, 0x10000
	s_add_i32 s56, 0, 0x14000
	v_lshl_or_b32 v152, s12, 6, v149
	s_mov_b32 s53, 0
	s_ashr_i32 s54, s86, 31
	v_mov_b32_e32 v139, v137
	v_add_u32_e32 v140, v2, v146
	v_mov_b32_e32 v141, v137
	v_add_u32_e32 v154, s55, v153
	v_add_u32_e32 v155, s56, v153
	v_add_u32_e32 v156, 0, v1
	v_lshlrev_b32_e32 v136, 1, v0
	s_mov_b32 s57, 0x40000
	s_mov_b64 s[12:13], 0x48000
	s_mov_b32 s58, 0x48000
	s_mov_b64 s[14:15], 0x50000
	s_mov_b32 s59, 0x50000
	s_mov_b64 s[16:17], 0x58000
	s_mov_b32 s60, 0x58000
	s_barrier
	s_branch .LBB0_1486

.LBB0_1499:
	v_readlane_b32 s12, v244, 0
	v_readlane_b32 s13, v244, 1
	v_readlane_b32 s14, v244, 2
	v_readlane_b32 s15, v244, 3
	v_readlane_b32 s16, v244, 4
	v_readlane_b32 s17, v244, 5
	v_readlane_b32 s18, v244, 6
	v_readlane_b32 s19, v244, 7
	s_mov_b64 s[12:13], s[16:17]
	s_mov_b64 s[14:15], s[18:19]
	s_add_u32 s4, s14, 0x15800000
	s_addc_u32 s5, s15, 0
	s_lshl_b32 s6, s6, 5
	s_and_b32 s14, s6, 0x60
	s_mov_b64 s[6:7], 0x80
	s_add_i32 m0, s35, 0x18000
	v_lshl_add_u64 v[6:7], v[6:7], 0, s[6:7]
	s_lshl_b32 s11, s10, 13
	s_waitcnt vmcnt(2)
	s_barrier
	global_load_lds_dwordx4 v[6:7], off
	v_lshl_add_u64 v[4:5], v[4:5], 0, s[6:7]
	s_add_i32 m0, s35, 0x1a000
	s_add_i32 s41, s35, 0x8000
	s_add_i32 s42, s35, 0xa000
	global_load_lds_dwordx4 v[4:5], off
	v_lshl_add_u64 v[0:1], v[0:1], 0, s[6:7]
	s_mov_b32 m0, s41
	s_add_u32 s12, s24, 0x40080
	global_load_lds_dwordx4 v[0:1], off
	v_lshl_add_u64 v[0:1], v[2:3], 0, s[6:7]
	s_mov_b32 m0, s42
	s_addc_u32 s13, s25, 0
	global_load_lds_dwordx4 v[0:1], off
	s_add_i32 m0, s35, 0x1c000
	v_lshl_add_u64 v[0:1], s[12:13], 0, v[130:131]
	global_load_lds_dwordx4 v[0:1], off
	v_lshl_add_u64 v[0:1], s[12:13], 0, v[134:135]
	s_add_i32 m0, s35, 0x1e000
	v_lshlrev_b32_e32 v2, 8, v182
	global_load_lds_dwordx4 v[0:1], off
	v_and_b32_e32 v2, 0x38000, v2
	v_lshlrev_b32_e32 v3, 11, v143
	v_or3_b32 v2, v142, v2, v3
	v_lshlrev_b32_e32 v1, 2, v149
	v_add_u32_e32 v138, v2, v146
	v_lshlrev_b32_e32 v2, 4, v147
	v_lshl_or_b32 v0, v149, 6, v150
	v_and_b32_e32 v1, 32, v1
	s_waitcnt vmcnt(6)
	s_cmpk_lt_u32 s9, 0x100
	v_and_b32_e32 v2, 0x78000, v2
	s_sext_i32_i8 s21, s8
	v_lshl_or_b32 v152, s10, 6, v149
	v_bitop3_b32 v1, v0, s11, v1 bitop3:0xde
	v_lshl_or_b32 v149, s14, 7, v151
	s_cselect_b64 s[8:9], -1, 0
	v_or_b32_e32 v0, s14, v148
	v_or3_b32 v2, v142, v2, v3
	s_add_i32 s44, 0, 0x10000
	s_add_i32 s45, 0, 0x14000
	s_ashr_i32 s43, s86, 31
	v_mov_b32_e32 v139, v137
	v_add_u32_e32 v140, v2, v146
	v_mov_b32_e32 v141, v137
	v_add_u32_e32 v142, s44, v149
	v_add_u32_e32 v143, s45, v149
	v_add_u32_e32 v146, 0, v1
	s_movk_i32 s46, 0x1400
	v_lshlrev_b32_e32 v136, 1, v0
	s_barrier
	s_branch .LBB0_1502

.LBB0_1712:
	s_cmpk_gt_i32 s89, 0x27f
	s_cbranch_scc1 .LBB0_1715
	v_lshlrev_b32_e32 v0, 4, v182
	v_readlane_b32 s4, v244, 0
	v_lshlrev_b32_e32 v2, 3, v182
	v_mbcnt_lo_u32_b32 v3, -1, 0
	v_and_b32_e32 v4, 0x600, v0
	v_mov_b32_e32 v5, 0
	v_readlane_b32 s10, v244, 6
	v_readlane_b32 s11, v244, 7
	v_and_b32_e32 v2, 0xf8, v2
	v_mbcnt_hi_u32_b32 v3, -1, v3
	v_lshl_add_u64 v[0:1], s[10:11], 0, v[4:5]
	v_lshlrev_b32_e32 v4, 1, v2
	v_and_b32_e32 v6, 64, v3
	v_lshl_add_u64 v[0:1], v[0:1], 0, v[4:5]
	v_xor_b32_e32 v4, 1, v3
	v_add_u32_e32 v10, 64, v6
	v_cmp_lt_i32_e32 vcc, v4, v10
	v_readlane_b32 s5, v244, 1
	v_readlane_b32 s6, v244, 2
	v_cndmask_b32_e32 v4, v3, v4, vcc
	v_lshlrev_b32_e32 v6, 2, v4
	v_xor_b32_e32 v4, 2, v3
	v_cmp_lt_i32_e32 vcc, v4, v10
	v_readlane_b32 s7, v244, 3
	v_readlane_b32 s8, v244, 4
	v_cndmask_b32_e32 v4, v3, v4, vcc
	v_lshlrev_b32_e32 v7, 2, v4
	v_xor_b32_e32 v4, 4, v3
	v_cmp_lt_i32_e32 vcc, v4, v10
	v_readlane_b32 s9, v244, 5
	v_readlane_b32 s4, v244, 31
	v_cndmask_b32_e32 v4, v3, v4, vcc
	v_lshlrev_b32_e32 v8, 2, v4
	v_xor_b32_e32 v4, 8, v3
	v_cmp_lt_i32_e32 vcc, v4, v10
	v_readlane_b32 s8, v244, 35
	v_readlane_b32 s9, v244, 36
	v_cndmask_b32_e32 v4, v3, v4, vcc
	v_lshlrev_b32_e32 v9, 2, v4
	v_xor_b32_e32 v4, 16, v3
	v_readlane_b32 s10, v244, 37
	v_readlane_b32 s11, v244, 38
	v_readlane_b32 s12, v244, 39
	v_readlane_b32 s13, v244, 40
	v_cmp_lt_i32_e32 vcc, v4, v10
	v_readlane_b32 s14, v244, 41
	v_readlane_b32 s15, v244, 42
	s_mov_b64 s[8:9], s[12:13]
	v_lshrrev_b32_e32 v11, 5, v182
	s_mov_b64 s[0:1], 0x15000000
	v_cndmask_b32_e32 v3, v3, v4, vcc
	v_lshlrev_b32_e32 v4, 2, v2
	v_readlane_b32 s5, v244, 32
	s_mov_b64 s[10:11], s[14:15]
	v_lshl_add_u64 v[0:1], v[0:1], 0, s[0:1]
	v_lshlrev_b32_e32 v10, 2, v3
	v_lshl_add_u64 v[2:3], s[10:11], 0, v[4:5]
	v_lshl_add_u64 v[4:5], s[8:9], 0, v[4:5]
	v_lshl_add_u32 v11, s89, 4, v11
	s_lshl_b32 s4, s86, 4
	v_mov_b32_e32 v12, 0x358637bd
	s_mov_b32 s5, 0xf800000
	v_mov_b32_e32 v13, 0x260
	v_readlane_b32 s6, v244, 33
	v_readlane_b32 s7, v244, 34
	v_readlane_b32 s16, v244, 43
	v_readlane_b32 s17, v244, 44
	v_readlane_b32 s18, v244, 45
	v_readlane_b32 s19, v244, 46

.Lxa_unit:
	s_and_b32 s0, s69, 31
	s_lshr_b32 s1, s69, 8
	s_lshl_b32 s1, s1, 5
	s_add_i32 s1, s1, s0
	s_mul_i32 s0, s1, 2731
	s_lshr_b32 s0, s0, 16
	s_mul_i32 s17, s0, 24
	s_sub_i32 s1, s1, s17
	s_bfe_u32 s17, s69, 0x30005
	s_mul_i32 s17, s17, 24
	s_add_i32 s1, s1, s17
	s_lshr_b32 s10, s1, 5
	s_sub_i32 s11, s1, 64
	s_lshr_b32 s11, s11, 4
	s_add_i32 s11, s11, 2
	s_cmp_lt_u32 s1, 64
	s_cselect_b32 s10, s10, s11
	s_lshl_b32 s11, s10, 19
	s_lshl_b32 s12, s0, 9
	s_add_u32 s11, s11, s12
	s_add_u32 s11, s11, 0x15000000
	s_add_u32 s6, s4, s11
	s_addc_u32 s7, s5, 0
	s_mul_i32 s11, s0, 0x140000
	s_lshl_b32 s12, s10, 9
	s_add_u32 s11, s11, s12
	s_add_u32 s11, s11, 0x15800000
	s_add_u32 s8, s4, s11
	s_addc_u32 s9, s5, 0
	s_lshl_b32 s12, s1, 19
	s_lshl_b32 s13, s0, 9
	s_add_u32 s12, s12, s13
	s_add_u32 s12, s12, 0x9000000
	s_add_u32 s14, s4, s12
	s_addc_u32 s15, s5, 0
	global_load_dwordx4 v[128:131], v224, s[6:7]
	s_add_u32 s6, s6, 0x8000
	s_addc_u32 s7, s7, 0
	global_load_dwordx4 v[132:135], v224, s[6:7]
	s_add_u32 s6, s6, 0x8000
	s_addc_u32 s7, s7, 0
	global_load_dwordx4 v[136:139], v224, s[6:7]
	s_add_u32 s6, s6, 0x8000
	s_addc_u32 s7, s7, 0
	global_load_dwordx4 v[140:143], v224, s[6:7]
	s_add_u32 s6, s6, 0x8000
	s_addc_u32 s7, s7, 0
	global_load_dwordx4 v[144:147], v224, s[6:7]
	s_add_u32 s6, s6, 0x8000
	s_addc_u32 s7, s7, 0
	global_load_dwordx4 v[148:151], v224, s[6:7]
	s_add_u32 s6, s6, 0x8000
	s_addc_u32 s7, s7, 0
	global_load_dwordx4 v[152:155], v224, s[6:7]
	s_add_u32 s6, s6, 0x8000
	s_addc_u32 s7, s7, 0
	global_load_dwordx4 v[156:159], v224, s[6:7]
	s_add_u32 s6, s6, 0x8000
	s_addc_u32 s7, s7, 0
	global_load_dwordx4 v[184:187], v224, s[6:7]
	s_add_u32 s6, s6, 0x8000
	s_addc_u32 s7, s7, 0
	global_load_dwordx4 v[188:191], v224, s[6:7]
	s_add_u32 s6, s6, 0x8000
	s_addc_u32 s7, s7, 0
	global_load_dwordx4 v[192:195], v224, s[6:7]
	s_add_u32 s6, s6, 0x8000
	s_addc_u32 s7, s7, 0
	global_load_dwordx4 v[196:199], v224, s[6:7]
	s_add_u32 s6, s6, 0x8000
	s_addc_u32 s7, s7, 0
	global_load_dwordx4 v[200:203], v224, s[6:7]
	s_add_u32 s6, s6, 0x8000
	s_addc_u32 s7, s7, 0
	global_load_dwordx4 v[204:207], v224, s[6:7]
	s_add_u32 s6, s6, 0x8000
	s_addc_u32 s7, s7, 0
	global_load_dwordx4 v[208:211], v224, s[6:7]
	s_add_u32 s6, s6, 0x8000
	s_addc_u32 s7, s7, 0
	global_load_dwordx4 v[212:215], v224, s[6:7]
	s_waitcnt vmcnt(12)
	ds_write_b128 v226, v[128:131] offset:0
	ds_write_b128 v226, v[132:135] offset:8448
	ds_write_b128 v226, v[136:139] offset:16896
	ds_write_b128 v226, v[140:143] offset:25344
	s_waitcnt vmcnt(8)
	ds_write_b128 v226, v[144:147] offset:33792
	ds_write_b128 v226, v[148:151] offset:42240
	ds_write_b128 v226, v[152:155] offset:50688
	ds_write_b128 v226, v[156:159] offset:59136
	s_waitcnt vmcnt(4)
	ds_write_b128 v227, v[184:187] offset:0
	ds_write_b128 v227, v[188:191] offset:8448
	ds_write_b128 v227, v[192:195] offset:16896
	ds_write_b128 v227, v[196:199] offset:25344
	s_waitcnt vmcnt(0)
	ds_write_b128 v227, v[200:203] offset:33792
	ds_write_b128 v227, v[204:207] offset:42240
	ds_write_b128 v227, v[208:211] offset:50688
	ds_write_b128 v227, v[212:215] offset:59136
	s_waitcnt vmcnt(0)
	v_fmamk_f32 v178, v247, 0x3b800000, v181
	v_fmamk_f32 v179, v248, 0x3b800000, v181
	v_rsq_f32_e32 v178, v178
	v_rsq_f32_e32 v179, v179
	v_mov_b32_e32 v176, 0
	v_mov_b32_e32 v177, 0
	v_mul_f32_e32 v178, 0x3db8aa3b, v178
	v_mul_f32_e32 v179, 0x3db8aa3b, v179
	s_waitcnt lgkmcnt(0)
	s_barrier
	v_mov_b32_e32 v233, v231
	ds_read_b128 v[128:131], v233 offset:0
	ds_read_b128 v[132:135], v233 offset:64
	ds_read_b128 v[136:139], v233 offset:128
	ds_read_b128 v[140:143], v233 offset:192
	ds_read_b128 v[144:147], v233 offset:256
	ds_read_b128 v[148:151], v233 offset:320
	ds_read_b128 v[152:155], v233 offset:384
	ds_read_b128 v[156:159], v233 offset:448
	s_waitcnt lgkmcnt(0)
	ds_read_b128 v[184:187], v233 offset:8448
	ds_read_b128 v[188:191], v233 offset:8512
	ds_read_b128 v[192:195], v233 offset:8576
	ds_read_b128 v[196:199], v233 offset:8640
	ds_read_b128 v[200:203], v233 offset:8704
	ds_read_b128 v[204:207], v233 offset:8768
	ds_read_b128 v[208:211], v233 offset:8832
	ds_read_b128 v[212:215], v233 offset:8896
	v_mfma_f32_16x16x32_bf16 v[160:163], v[128:131], v[0:3], 0
	v_mfma_f32_16x16x32_bf16 v[164:167], v[128:131], v[32:35], 0
	v_mfma_f32_16x16x32_bf16 v[160:163], v[132:135], v[4:7], v[160:163]
	v_mfma_f32_16x16x32_bf16 v[164:167], v[132:135], v[36:39], v[164:167]
	v_mfma_f32_16x16x32_bf16 v[160:163], v[136:139], v[8:11], v[160:163]
	v_mfma_f32_16x16x32_bf16 v[164:167], v[136:139], v[40:43], v[164:167]
	v_mfma_f32_16x16x32_bf16 v[160:163], v[140:143], v[12:15], v[160:163]
	v_mfma_f32_16x16x32_bf16 v[164:167], v[140:143], v[44:47], v[164:167]
	v_mfma_f32_16x16x32_bf16 v[160:163], v[144:147], v[16:19], v[160:163]
	v_mfma_f32_16x16x32_bf16 v[164:167], v[144:147], v[48:51], v[164:167]
	v_mfma_f32_16x16x32_bf16 v[160:163], v[148:151], v[20:23], v[160:163]
	v_mfma_f32_16x16x32_bf16 v[164:167], v[148:151], v[52:55], v[164:167]
	v_mfma_f32_16x16x32_bf16 v[160:163], v[152:155], v[24:27], v[160:163]
	v_mfma_f32_16x16x32_bf16 v[164:167], v[152:155], v[56:59], v[164:167]
	v_mfma_f32_16x16x32_bf16 v[160:163], v[156:159], v[28:31], v[160:163]
	v_mfma_f32_16x16x32_bf16 v[164:167], v[156:159], v[60:63], v[164:167]
	s_waitcnt lgkmcnt(0)
	ds_read_b128 v[128:131], v233 offset:16896
	ds_read_b128 v[132:135], v233 offset:16960
	ds_read_b128 v[136:139], v233 offset:17024
	ds_read_b128 v[140:143], v233 offset:17088
	ds_read_b128 v[144:147], v233 offset:17152
	ds_read_b128 v[148:151], v233 offset:17216
	ds_read_b128 v[152:155], v233 offset:17280
	ds_read_b128 v[156:159], v233 offset:17344
	v_mfma_f32_16x16x32_bf16 v[168:171], v[184:187], v[0:3], 0
	v_fma_f32 v216, v160, v178, -v180
	v_fma_f32 v217, v161, v178, -v180
	v_mfma_f32_16x16x32_bf16 v[172:175], v[184:187], v[32:35], 0
	v_fma_f32 v218, v162, v178, -v180
	v_fma_f32 v219, v163, v178, -v180
	v_mfma_f32_16x16x32_bf16 v[168:171], v[188:191], v[4:7], v[168:171]
	v_exp_f32_e32 v216, v216
	v_exp_f32_e32 v217, v217
	v_mfma_f32_16x16x32_bf16 v[172:175], v[188:191], v[36:39], v[172:175]
	v_exp_f32_e32 v218, v218
	v_exp_f32_e32 v219, v219
	v_mfma_f32_16x16x32_bf16 v[168:171], v[192:195], v[8:11], v[168:171]
	v_fma_f32 v220, v164, v179, -v180
	v_fma_f32 v221, v165, v179, -v180
	v_mfma_f32_16x16x32_bf16 v[172:175], v[192:195], v[40:43], v[172:175]
	v_fma_f32 v222, v166, v179, -v180
	v_fma_f32 v223, v167, v179, -v180
	v_mfma_f32_16x16x32_bf16 v[168:171], v[196:199], v[12:15], v[168:171]
	v_exp_f32_e32 v220, v220
	v_exp_f32_e32 v221, v221
	v_mfma_f32_16x16x32_bf16 v[172:175], v[196:199], v[44:47], v[172:175]
	v_exp_f32_e32 v222, v222
	v_exp_f32_e32 v223, v223
	v_mfma_f32_16x16x32_bf16 v[168:171], v[200:203], v[16:19], v[168:171]
	v_add_f32_e32 v176, v176, v216
	v_add_f32_e32 v176, v176, v217
	v_mfma_f32_16x16x32_bf16 v[172:175], v[200:203], v[48:51], v[172:175]
	v_cvt_pk_bf16_f32 v64, v216, v217
	v_add_f32_e32 v176, v176, v218
	v_mfma_f32_16x16x32_bf16 v[168:171], v[204:207], v[20:23], v[168:171]
	v_add_f32_e32 v176, v176, v219
	v_cvt_pk_bf16_f32 v65, v218, v219
	v_mfma_f32_16x16x32_bf16 v[172:175], v[204:207], v[52:55], v[172:175]
	v_add_f32_e32 v177, v177, v220
	v_add_f32_e32 v177, v177, v221
	v_mfma_f32_16x16x32_bf16 v[168:171], v[208:211], v[24:27], v[168:171]
	v_cvt_pk_bf16_f32 v96, v220, v221
	v_add_f32_e32 v177, v177, v222
	v_mfma_f32_16x16x32_bf16 v[172:175], v[208:211], v[56:59], v[172:175]
	v_add_f32_e32 v177, v177, v223
	v_cvt_pk_bf16_f32 v97, v222, v223
	v_mfma_f32_16x16x32_bf16 v[168:171], v[212:215], v[28:31], v[168:171]
	v_mfma_f32_16x16x32_bf16 v[172:175], v[212:215], v[60:63], v[172:175]
	s_waitcnt lgkmcnt(0)
	ds_read_b128 v[184:187], v233 offset:25344
	ds_read_b128 v[188:191], v233 offset:25408
	ds_read_b128 v[192:195], v233 offset:25472
	ds_read_b128 v[196:199], v233 offset:25536
	ds_read_b128 v[200:203], v233 offset:25600
	ds_read_b128 v[204:207], v233 offset:25664
	ds_read_b128 v[208:211], v233 offset:25728
	ds_read_b128 v[212:215], v233 offset:25792
	v_mfma_f32_16x16x32_bf16 v[160:163], v[128:131], v[0:3], 0
	v_fma_f32 v216, v168, v178, -v180
	v_fma_f32 v217, v169, v178, -v180
	v_mfma_f32_16x16x32_bf16 v[164:167], v[128:131], v[32:35], 0
	v_fma_f32 v218, v170, v178, -v180
	v_fma_f32 v219, v171, v178, -v180
	v_mfma_f32_16x16x32_bf16 v[160:163], v[132:135], v[4:7], v[160:163]
	v_exp_f32_e32 v216, v216
	v_exp_f32_e32 v217, v217
	v_mfma_f32_16x16x32_bf16 v[164:167], v[132:135], v[36:39], v[164:167]
	v_exp_f32_e32 v218, v218
	v_exp_f32_e32 v219, v219
	v_mfma_f32_16x16x32_bf16 v[160:163], v[136:139], v[8:11], v[160:163]
	v_fma_f32 v220, v172, v179, -v180
	v_fma_f32 v221, v173, v179, -v180
	v_mfma_f32_16x16x32_bf16 v[164:167], v[136:139], v[40:43], v[164:167]
	v_fma_f32 v222, v174, v179, -v180
	v_fma_f32 v223, v175, v179, -v180
	v_mfma_f32_16x16x32_bf16 v[160:163], v[140:143], v[12:15], v[160:163]
	v_exp_f32_e32 v220, v220
	v_exp_f32_e32 v221, v221
	v_mfma_f32_16x16x32_bf16 v[164:167], v[140:143], v[44:47], v[164:167]
	v_exp_f32_e32 v222, v222
	v_exp_f32_e32 v223, v223
	v_mfma_f32_16x16x32_bf16 v[160:163], v[144:147], v[16:19], v[160:163]
	v_add_f32_e32 v176, v176, v216
	v_add_f32_e32 v176, v176, v217
	v_mfma_f32_16x16x32_bf16 v[164:167], v[144:147], v[48:51], v[164:167]
	v_cvt_pk_bf16_f32 v66, v216, v217
	v_add_f32_e32 v176, v176, v218
	v_mfma_f32_16x16x32_bf16 v[160:163], v[148:151], v[20:23], v[160:163]
	v_add_f32_e32 v176, v176, v219
	v_cvt_pk_bf16_f32 v67, v218, v219
	v_mfma_f32_16x16x32_bf16 v[164:167], v[148:151], v[52:55], v[164:167]
	v_add_f32_e32 v177, v177, v220
	v_add_f32_e32 v177, v177, v221
	v_mfma_f32_16x16x32_bf16 v[160:163], v[152:155], v[24:27], v[160:163]
	v_cvt_pk_bf16_f32 v98, v220, v221
	v_add_f32_e32 v177, v177, v222
	v_mfma_f32_16x16x32_bf16 v[164:167], v[152:155], v[56:59], v[164:167]
	v_add_f32_e32 v177, v177, v223
	v_cvt_pk_bf16_f32 v99, v222, v223
	v_mfma_f32_16x16x32_bf16 v[160:163], v[156:159], v[28:31], v[160:163]
	v_mfma_f32_16x16x32_bf16 v[164:167], v[156:159], v[60:63], v[164:167]
	s_waitcnt lgkmcnt(0)
	ds_read_b128 v[128:131], v233 offset:33792
	ds_read_b128 v[132:135], v233 offset:33856
	ds_read_b128 v[136:139], v233 offset:33920
	ds_read_b128 v[140:143], v233 offset:33984
	ds_read_b128 v[144:147], v233 offset:34048
	ds_read_b128 v[148:151], v233 offset:34112
	ds_read_b128 v[152:155], v233 offset:34176
	ds_read_b128 v[156:159], v233 offset:34240
	v_mfma_f32_16x16x32_bf16 v[168:171], v[184:187], v[0:3], 0
	v_fma_f32 v216, v160, v178, -v180
	v_fma_f32 v217, v161, v178, -v180
	v_mfma_f32_16x16x32_bf16 v[172:175], v[184:187], v[32:35], 0
	v_fma_f32 v218, v162, v178, -v180
	v_fma_f32 v219, v163, v178, -v180
	v_mfma_f32_16x16x32_bf16 v[168:171], v[188:191], v[4:7], v[168:171]
	v_exp_f32_e32 v216, v216
	v_exp_f32_e32 v217, v217
	v_mfma_f32_16x16x32_bf16 v[172:175], v[188:191], v[36:39], v[172:175]
	v_exp_f32_e32 v218, v218
	v_exp_f32_e32 v219, v219
	v_mfma_f32_16x16x32_bf16 v[168:171], v[192:195], v[8:11], v[168:171]
	v_fma_f32 v220, v164, v179, -v180
	v_fma_f32 v221, v165, v179, -v180
	v_mfma_f32_16x16x32_bf16 v[172:175], v[192:195], v[40:43], v[172:175]
	v_fma_f32 v222, v166, v179, -v180
	v_fma_f32 v223, v167, v179, -v180
	v_mfma_f32_16x16x32_bf16 v[168:171], v[196:199], v[12:15], v[168:171]
	v_exp_f32_e32 v220, v220
	v_exp_f32_e32 v221, v221
	v_mfma_f32_16x16x32_bf16 v[172:175], v[196:199], v[44:47], v[172:175]
	v_exp_f32_e32 v222, v222
	v_exp_f32_e32 v223, v223
	v_mfma_f32_16x16x32_bf16 v[168:171], v[200:203], v[16:19], v[168:171]
	v_add_f32_e32 v176, v176, v216
	v_add_f32_e32 v176, v176, v217
	v_mfma_f32_16x16x32_bf16 v[172:175], v[200:203], v[48:51], v[172:175]
	v_cvt_pk_bf16_f32 v68, v216, v217
	v_add_f32_e32 v176, v176, v218
	v_mfma_f32_16x16x32_bf16 v[168:171], v[204:207], v[20:23], v[168:171]
	v_add_f32_e32 v176, v176, v219
	v_cvt_pk_bf16_f32 v69, v218, v219
	v_mfma_f32_16x16x32_bf16 v[172:175], v[204:207], v[52:55], v[172:175]
	v_add_f32_e32 v177, v177, v220
	v_add_f32_e32 v177, v177, v221
	v_mfma_f32_16x16x32_bf16 v[168:171], v[208:211], v[24:27], v[168:171]
	v_cvt_pk_bf16_f32 v100, v220, v221
	v_add_f32_e32 v177, v177, v222
	v_mfma_f32_16x16x32_bf16 v[172:175], v[208:211], v[56:59], v[172:175]
	v_add_f32_e32 v177, v177, v223
	v_cvt_pk_bf16_f32 v101, v222, v223
	v_mfma_f32_16x16x32_bf16 v[168:171], v[212:215], v[28:31], v[168:171]
	v_mfma_f32_16x16x32_bf16 v[172:175], v[212:215], v[60:63], v[172:175]
	s_waitcnt lgkmcnt(0)
	ds_read_b128 v[184:187], v233 offset:42240
	ds_read_b128 v[188:191], v233 offset:42304
	ds_read_b128 v[192:195], v233 offset:42368
	ds_read_b128 v[196:199], v233 offset:42432
	ds_read_b128 v[200:203], v233 offset:42496
	ds_read_b128 v[204:207], v233 offset:42560
	ds_read_b128 v[208:211], v233 offset:42624
	ds_read_b128 v[212:215], v233 offset:42688
	v_mfma_f32_16x16x32_bf16 v[160:163], v[128:131], v[0:3], 0
	v_fma_f32 v216, v168, v178, -v180
	v_fma_f32 v217, v169, v178, -v180
	v_mfma_f32_16x16x32_bf16 v[164:167], v[128:131], v[32:35], 0
	v_fma_f32 v218, v170, v178, -v180
	v_fma_f32 v219, v171, v178, -v180
	v_mfma_f32_16x16x32_bf16 v[160:163], v[132:135], v[4:7], v[160:163]
	v_exp_f32_e32 v216, v216
	v_exp_f32_e32 v217, v217
	v_mfma_f32_16x16x32_bf16 v[164:167], v[132:135], v[36:39], v[164:167]
	v_exp_f32_e32 v218, v218
	v_exp_f32_e32 v219, v219
	v_mfma_f32_16x16x32_bf16 v[160:163], v[136:139], v[8:11], v[160:163]
	v_fma_f32 v220, v172, v179, -v180
	v_fma_f32 v221, v173, v179, -v180
	v_mfma_f32_16x16x32_bf16 v[164:167], v[136:139], v[40:43], v[164:167]
	v_fma_f32 v222, v174, v179, -v180
	v_fma_f32 v223, v175, v179, -v180
	v_mfma_f32_16x16x32_bf16 v[160:163], v[140:143], v[12:15], v[160:163]
	v_exp_f32_e32 v220, v220
	v_exp_f32_e32 v221, v221
	v_mfma_f32_16x16x32_bf16 v[164:167], v[140:143], v[44:47], v[164:167]
	v_exp_f32_e32 v222, v222
	v_exp_f32_e32 v223, v223
	v_mfma_f32_16x16x32_bf16 v[160:163], v[144:147], v[16:19], v[160:163]
	v_add_f32_e32 v176, v176, v216
	v_add_f32_e32 v176, v176, v217
	v_mfma_f32_16x16x32_bf16 v[164:167], v[144:147], v[48:51], v[164:167]
	v_cvt_pk_bf16_f32 v70, v216, v217
	v_add_f32_e32 v176, v176, v218
	v_mfma_f32_16x16x32_bf16 v[160:163], v[148:151], v[20:23], v[160:163]
	v_add_f32_e32 v176, v176, v219
	v_cvt_pk_bf16_f32 v71, v218, v219
	v_mfma_f32_16x16x32_bf16 v[164:167], v[148:151], v[52:55], v[164:167]
	v_add_f32_e32 v177, v177, v220
	v_add_f32_e32 v177, v177, v221
	v_mfma_f32_16x16x32_bf16 v[160:163], v[152:155], v[24:27], v[160:163]
	v_cvt_pk_bf16_f32 v102, v220, v221
	v_add_f32_e32 v177, v177, v222
	v_mfma_f32_16x16x32_bf16 v[164:167], v[152:155], v[56:59], v[164:167]
	v_add_f32_e32 v177, v177, v223
	v_cvt_pk_bf16_f32 v103, v222, v223
	v_mfma_f32_16x16x32_bf16 v[160:163], v[156:159], v[28:31], v[160:163]
	v_mfma_f32_16x16x32_bf16 v[164:167], v[156:159], v[60:63], v[164:167]
	s_waitcnt lgkmcnt(0)
	ds_read_b128 v[128:131], v233 offset:50688
	ds_read_b128 v[132:135], v233 offset:50752
	ds_read_b128 v[136:139], v233 offset:50816
	ds_read_b128 v[140:143], v233 offset:50880
	ds_read_b128 v[144:147], v233 offset:50944
	ds_read_b128 v[148:151], v233 offset:51008
	ds_read_b128 v[152:155], v233 offset:51072
	ds_read_b128 v[156:159], v233 offset:51136
	v_mfma_f32_16x16x32_bf16 v[168:171], v[184:187], v[0:3], 0
	v_fma_f32 v216, v160, v178, -v180
	v_fma_f32 v217, v161, v178, -v180
	v_mfma_f32_16x16x32_bf16 v[172:175], v[184:187], v[32:35], 0
	v_fma_f32 v218, v162, v178, -v180
	v_fma_f32 v219, v163, v178, -v180
	v_mfma_f32_16x16x32_bf16 v[168:171], v[188:191], v[4:7], v[168:171]
	v_exp_f32_e32 v216, v216
	v_exp_f32_e32 v217, v217
	v_mfma_f32_16x16x32_bf16 v[172:175], v[188:191], v[36:39], v[172:175]
	v_exp_f32_e32 v218, v218
	v_exp_f32_e32 v219, v219
	v_mfma_f32_16x16x32_bf16 v[168:171], v[192:195], v[8:11], v[168:171]
	v_fma_f32 v220, v164, v179, -v180
	v_fma_f32 v221, v165, v179, -v180
	v_mfma_f32_16x16x32_bf16 v[172:175], v[192:195], v[40:43], v[172:175]
	v_fma_f32 v222, v166, v179, -v180
	v_fma_f32 v223, v167, v179, -v180
	v_mfma_f32_16x16x32_bf16 v[168:171], v[196:199], v[12:15], v[168:171]
	v_exp_f32_e32 v220, v220
	v_exp_f32_e32 v221, v221
	v_mfma_f32_16x16x32_bf16 v[172:175], v[196:199], v[44:47], v[172:175]
	v_exp_f32_e32 v222, v222
	v_exp_f32_e32 v223, v223
	v_mfma_f32_16x16x32_bf16 v[168:171], v[200:203], v[16:19], v[168:171]
	v_add_f32_e32 v176, v176, v216
	v_add_f32_e32 v176, v176, v217
	v_mfma_f32_16x16x32_bf16 v[172:175], v[200:203], v[48:51], v[172:175]
	v_cvt_pk_bf16_f32 v72, v216, v217
	v_add_f32_e32 v176, v176, v218
	v_mfma_f32_16x16x32_bf16 v[168:171], v[204:207], v[20:23], v[168:171]
	v_add_f32_e32 v176, v176, v219
	v_cvt_pk_bf16_f32 v73, v218, v219
	v_mfma_f32_16x16x32_bf16 v[172:175], v[204:207], v[52:55], v[172:175]
	v_add_f32_e32 v177, v177, v220
	v_add_f32_e32 v177, v177, v221
	v_mfma_f32_16x16x32_bf16 v[168:171], v[208:211], v[24:27], v[168:171]
	v_cvt_pk_bf16_f32 v104, v220, v221
	v_add_f32_e32 v177, v177, v222
	v_mfma_f32_16x16x32_bf16 v[172:175], v[208:211], v[56:59], v[172:175]
	v_add_f32_e32 v177, v177, v223
	v_cvt_pk_bf16_f32 v105, v222, v223
	v_mfma_f32_16x16x32_bf16 v[168:171], v[212:215], v[28:31], v[168:171]
	v_mfma_f32_16x16x32_bf16 v[172:175], v[212:215], v[60:63], v[172:175]
	s_waitcnt lgkmcnt(0)
	v_add_u32_e32 v233, 59136, v233
	ds_read_b128 v[184:187], v233 offset:0
	ds_read_b128 v[188:191], v233 offset:64
	ds_read_b128 v[192:195], v233 offset:128
	ds_read_b128 v[196:199], v233 offset:192
	ds_read_b128 v[200:203], v233 offset:256
	ds_read_b128 v[204:207], v233 offset:320
	ds_read_b128 v[208:211], v233 offset:384
	ds_read_b128 v[212:215], v233 offset:448
	v_mfma_f32_16x16x32_bf16 v[160:163], v[128:131], v[0:3], 0
	v_fma_f32 v216, v168, v178, -v180
	v_fma_f32 v217, v169, v178, -v180
	v_mfma_f32_16x16x32_bf16 v[164:167], v[128:131], v[32:35], 0
	v_fma_f32 v218, v170, v178, -v180
	v_fma_f32 v219, v171, v178, -v180
	v_mfma_f32_16x16x32_bf16 v[160:163], v[132:135], v[4:7], v[160:163]
	v_exp_f32_e32 v216, v216
	v_exp_f32_e32 v217, v217
	v_mfma_f32_16x16x32_bf16 v[164:167], v[132:135], v[36:39], v[164:167]
	v_exp_f32_e32 v218, v218
	v_exp_f32_e32 v219, v219
	v_mfma_f32_16x16x32_bf16 v[160:163], v[136:139], v[8:11], v[160:163]
	v_fma_f32 v220, v172, v179, -v180
	v_fma_f32 v221, v173, v179, -v180
	v_mfma_f32_16x16x32_bf16 v[164:167], v[136:139], v[40:43], v[164:167]
	v_fma_f32 v222, v174, v179, -v180
	v_fma_f32 v223, v175, v179, -v180
	v_mfma_f32_16x16x32_bf16 v[160:163], v[140:143], v[12:15], v[160:163]
	v_exp_f32_e32 v220, v220
	v_exp_f32_e32 v221, v221
	v_mfma_f32_16x16x32_bf16 v[164:167], v[140:143], v[44:47], v[164:167]
	v_exp_f32_e32 v222, v222
	v_exp_f32_e32 v223, v223
	v_mfma_f32_16x16x32_bf16 v[160:163], v[144:147], v[16:19], v[160:163]
	v_add_f32_e32 v176, v176, v216
	v_add_f32_e32 v176, v176, v217
	v_mfma_f32_16x16x32_bf16 v[164:167], v[144:147], v[48:51], v[164:167]
	v_cvt_pk_bf16_f32 v74, v216, v217
	v_add_f32_e32 v176, v176, v218
	v_mfma_f32_16x16x32_bf16 v[160:163], v[148:151], v[20:23], v[160:163]
	v_add_f32_e32 v176, v176, v219
	v_cvt_pk_bf16_f32 v75, v218, v219
	v_mfma_f32_16x16x32_bf16 v[164:167], v[148:151], v[52:55], v[164:167]
	v_add_f32_e32 v177, v177, v220
	v_add_f32_e32 v177, v177, v221
	v_mfma_f32_16x16x32_bf16 v[160:163], v[152:155], v[24:27], v[160:163]
	v_cvt_pk_bf16_f32 v106, v220, v221
	v_add_f32_e32 v177, v177, v222
	v_mfma_f32_16x16x32_bf16 v[164:167], v[152:155], v[56:59], v[164:167]
	v_add_f32_e32 v177, v177, v223
	v_cvt_pk_bf16_f32 v107, v222, v223
	v_mfma_f32_16x16x32_bf16 v[160:163], v[156:159], v[28:31], v[160:163]
	v_mfma_f32_16x16x32_bf16 v[164:167], v[156:159], v[60:63], v[164:167]
	s_waitcnt lgkmcnt(0)
	ds_read_b128 v[128:131], v233 offset:8448
	ds_read_b128 v[132:135], v233 offset:8512
	ds_read_b128 v[136:139], v233 offset:8576
	ds_read_b128 v[140:143], v233 offset:8640
	ds_read_b128 v[144:147], v233 offset:8704
	ds_read_b128 v[148:151], v233 offset:8768
	ds_read_b128 v[152:155], v233 offset:8832
	ds_read_b128 v[156:159], v233 offset:8896
	v_mfma_f32_16x16x32_bf16 v[168:171], v[184:187], v[0:3], 0
	v_fma_f32 v216, v160, v178, -v180
	v_fma_f32 v217, v161, v178, -v180
	v_mfma_f32_16x16x32_bf16 v[172:175], v[184:187], v[32:35], 0
	v_fma_f32 v218, v162, v178, -v180
	v_fma_f32 v219, v163, v178, -v180
	v_mfma_f32_16x16x32_bf16 v[168:171], v[188:191], v[4:7], v[168:171]
	v_exp_f32_e32 v216, v216
	v_exp_f32_e32 v217, v217
	v_mfma_f32_16x16x32_bf16 v[172:175], v[188:191], v[36:39], v[172:175]
	v_exp_f32_e32 v218, v218
	v_exp_f32_e32 v219, v219
	v_mfma_f32_16x16x32_bf16 v[168:171], v[192:195], v[8:11], v[168:171]
	v_fma_f32 v220, v164, v179, -v180
	v_fma_f32 v221, v165, v179, -v180
	v_mfma_f32_16x16x32_bf16 v[172:175], v[192:195], v[40:43], v[172:175]
	v_fma_f32 v222, v166, v179, -v180
	v_fma_f32 v223, v167, v179, -v180
	v_mfma_f32_16x16x32_bf16 v[168:171], v[196:199], v[12:15], v[168:171]
	v_exp_f32_e32 v220, v220
	v_exp_f32_e32 v221, v221
	v_mfma_f32_16x16x32_bf16 v[172:175], v[196:199], v[44:47], v[172:175]
	v_exp_f32_e32 v222, v222
	v_exp_f32_e32 v223, v223
	v_mfma_f32_16x16x32_bf16 v[168:171], v[200:203], v[16:19], v[168:171]
	v_add_f32_e32 v176, v176, v216
	v_add_f32_e32 v176, v176, v217
	v_mfma_f32_16x16x32_bf16 v[172:175], v[200:203], v[48:51], v[172:175]
	v_cvt_pk_bf16_f32 v76, v216, v217
	v_add_f32_e32 v176, v176, v218
	v_mfma_f32_16x16x32_bf16 v[168:171], v[204:207], v[20:23], v[168:171]
	v_add_f32_e32 v176, v176, v219
	v_cvt_pk_bf16_f32 v77, v218, v219
	v_mfma_f32_16x16x32_bf16 v[172:175], v[204:207], v[52:55], v[172:175]
	v_add_f32_e32 v177, v177, v220
	v_add_f32_e32 v177, v177, v221
	v_mfma_f32_16x16x32_bf16 v[168:171], v[208:211], v[24:27], v[168:171]
	v_cvt_pk_bf16_f32 v108, v220, v221
	v_add_f32_e32 v177, v177, v222
	v_mfma_f32_16x16x32_bf16 v[172:175], v[208:211], v[56:59], v[172:175]
	v_add_f32_e32 v177, v177, v223
	v_cvt_pk_bf16_f32 v109, v222, v223
	v_mfma_f32_16x16x32_bf16 v[168:171], v[212:215], v[28:31], v[168:171]
	v_mfma_f32_16x16x32_bf16 v[172:175], v[212:215], v[60:63], v[172:175]
	s_waitcnt lgkmcnt(0)
	ds_read_b128 v[184:187], v233 offset:16896
	ds_read_b128 v[188:191], v233 offset:16960
	ds_read_b128 v[192:195], v233 offset:17024
	ds_read_b128 v[196:199], v233 offset:17088
	ds_read_b128 v[200:203], v233 offset:17152
	ds_read_b128 v[204:207], v233 offset:17216
	ds_read_b128 v[208:211], v233 offset:17280
	ds_read_b128 v[212:215], v233 offset:17344
	v_mfma_f32_16x16x32_bf16 v[160:163], v[128:131], v[0:3], 0
	v_fma_f32 v216, v168, v178, -v180
	v_fma_f32 v217, v169, v178, -v180
	v_mfma_f32_16x16x32_bf16 v[164:167], v[128:131], v[32:35], 0
	v_fma_f32 v218, v170, v178, -v180
	v_fma_f32 v219, v171, v178, -v180
	v_mfma_f32_16x16x32_bf16 v[160:163], v[132:135], v[4:7], v[160:163]
	v_exp_f32_e32 v216, v216
	v_exp_f32_e32 v217, v217
	v_mfma_f32_16x16x32_bf16 v[164:167], v[132:135], v[36:39], v[164:167]
	v_exp_f32_e32 v218, v218
	v_exp_f32_e32 v219, v219
	v_mfma_f32_16x16x32_bf16 v[160:163], v[136:139], v[8:11], v[160:163]
	v_fma_f32 v220, v172, v179, -v180
	v_fma_f32 v221, v173, v179, -v180
	v_mfma_f32_16x16x32_bf16 v[164:167], v[136:139], v[40:43], v[164:167]
	v_fma_f32 v222, v174, v179, -v180
	v_fma_f32 v223, v175, v179, -v180
	v_mfma_f32_16x16x32_bf16 v[160:163], v[140:143], v[12:15], v[160:163]
	v_exp_f32_e32 v220, v220
	v_exp_f32_e32 v221, v221
	v_mfma_f32_16x16x32_bf16 v[164:167], v[140:143], v[44:47], v[164:167]
	v_exp_f32_e32 v222, v222
	v_exp_f32_e32 v223, v223
	v_mfma_f32_16x16x32_bf16 v[160:163], v[144:147], v[16:19], v[160:163]
	v_add_f32_e32 v176, v176, v216
	v_add_f32_e32 v176, v176, v217
	v_mfma_f32_16x16x32_bf16 v[164:167], v[144:147], v[48:51], v[164:167]
	v_cvt_pk_bf16_f32 v78, v216, v217
	v_add_f32_e32 v176, v176, v218
	v_mfma_f32_16x16x32_bf16 v[160:163], v[148:151], v[20:23], v[160:163]
	v_add_f32_e32 v176, v176, v219
	v_cvt_pk_bf16_f32 v79, v218, v219
	v_mfma_f32_16x16x32_bf16 v[164:167], v[148:151], v[52:55], v[164:167]
	v_add_f32_e32 v177, v177, v220
	v_add_f32_e32 v177, v177, v221
	v_mfma_f32_16x16x32_bf16 v[160:163], v[152:155], v[24:27], v[160:163]
	v_cvt_pk_bf16_f32 v110, v220, v221
	v_add_f32_e32 v177, v177, v222
	v_mfma_f32_16x16x32_bf16 v[164:167], v[152:155], v[56:59], v[164:167]
	v_add_f32_e32 v177, v177, v223
	v_cvt_pk_bf16_f32 v111, v222, v223
	v_mfma_f32_16x16x32_bf16 v[160:163], v[156:159], v[28:31], v[160:163]
	v_mfma_f32_16x16x32_bf16 v[164:167], v[156:159], v[60:63], v[164:167]
	s_waitcnt lgkmcnt(0)
	ds_read_b128 v[128:131], v233 offset:25344
	ds_read_b128 v[132:135], v233 offset:25408
	ds_read_b128 v[136:139], v233 offset:25472
	ds_read_b128 v[140:143], v233 offset:25536
	ds_read_b128 v[144:147], v233 offset:25600
	ds_read_b128 v[148:151], v233 offset:25664
	ds_read_b128 v[152:155], v233 offset:25728
	ds_read_b128 v[156:159], v233 offset:25792
	v_mfma_f32_16x16x32_bf16 v[168:171], v[184:187], v[0:3], 0
	v_fma_f32 v216, v160, v178, -v180
	v_fma_f32 v217, v161, v178, -v180
	v_mfma_f32_16x16x32_bf16 v[172:175], v[184:187], v[32:35], 0
	v_fma_f32 v218, v162, v178, -v180
	v_fma_f32 v219, v163, v178, -v180
	v_mfma_f32_16x16x32_bf16 v[168:171], v[188:191], v[4:7], v[168:171]
	v_exp_f32_e32 v216, v216
	v_exp_f32_e32 v217, v217
	v_mfma_f32_16x16x32_bf16 v[172:175], v[188:191], v[36:39], v[172:175]
	v_exp_f32_e32 v218, v218
	v_exp_f32_e32 v219, v219
	v_mfma_f32_16x16x32_bf16 v[168:171], v[192:195], v[8:11], v[168:171]
	v_fma_f32 v220, v164, v179, -v180
	v_fma_f32 v221, v165, v179, -v180
	v_mfma_f32_16x16x32_bf16 v[172:175], v[192:195], v[40:43], v[172:175]
	v_fma_f32 v222, v166, v179, -v180
	v_fma_f32 v223, v167, v179, -v180
	v_mfma_f32_16x16x32_bf16 v[168:171], v[196:199], v[12:15], v[168:171]
	v_exp_f32_e32 v220, v220
	v_exp_f32_e32 v221, v221
	v_mfma_f32_16x16x32_bf16 v[172:175], v[196:199], v[44:47], v[172:175]
	v_exp_f32_e32 v222, v222
	v_exp_f32_e32 v223, v223
	v_mfma_f32_16x16x32_bf16 v[168:171], v[200:203], v[16:19], v[168:171]
	v_add_f32_e32 v176, v176, v216
	v_add_f32_e32 v176, v176, v217
	v_mfma_f32_16x16x32_bf16 v[172:175], v[200:203], v[48:51], v[172:175]
	v_cvt_pk_bf16_f32 v80, v216, v217
	v_add_f32_e32 v176, v176, v218
	v_mfma_f32_16x16x32_bf16 v[168:171], v[204:207], v[20:23], v[168:171]
	v_add_f32_e32 v176, v176, v219
	v_cvt_pk_bf16_f32 v81, v218, v219
	v_mfma_f32_16x16x32_bf16 v[172:175], v[204:207], v[52:55], v[172:175]
	v_add_f32_e32 v177, v177, v220
	v_add_f32_e32 v177, v177, v221
	v_mfma_f32_16x16x32_bf16 v[168:171], v[208:211], v[24:27], v[168:171]
	v_cvt_pk_bf16_f32 v112, v220, v221
	v_add_f32_e32 v177, v177, v222
	v_mfma_f32_16x16x32_bf16 v[172:175], v[208:211], v[56:59], v[172:175]
	v_add_f32_e32 v177, v177, v223
	v_cvt_pk_bf16_f32 v113, v222, v223
	v_mfma_f32_16x16x32_bf16 v[168:171], v[212:215], v[28:31], v[168:171]
	v_mfma_f32_16x16x32_bf16 v[172:175], v[212:215], v[60:63], v[172:175]
	s_waitcnt lgkmcnt(0)
	ds_read_b128 v[184:187], v233 offset:33792
	ds_read_b128 v[188:191], v233 offset:33856
	ds_read_b128 v[192:195], v233 offset:33920
	ds_read_b128 v[196:199], v233 offset:33984
	ds_read_b128 v[200:203], v233 offset:34048
	ds_read_b128 v[204:207], v233 offset:34112
	ds_read_b128 v[208:211], v233 offset:34176
	ds_read_b128 v[212:215], v233 offset:34240
	v_mfma_f32_16x16x32_bf16 v[160:163], v[128:131], v[0:3], 0
	v_fma_f32 v216, v168, v178, -v180
	v_fma_f32 v217, v169, v178, -v180
	v_mfma_f32_16x16x32_bf16 v[164:167], v[128:131], v[32:35], 0
	v_fma_f32 v218, v170, v178, -v180
	v_fma_f32 v219, v171, v178, -v180
	v_mfma_f32_16x16x32_bf16 v[160:163], v[132:135], v[4:7], v[160:163]
	v_exp_f32_e32 v216, v216
	v_exp_f32_e32 v217, v217
	v_mfma_f32_16x16x32_bf16 v[164:167], v[132:135], v[36:39], v[164:167]
	v_exp_f32_e32 v218, v218
	v_exp_f32_e32 v219, v219
	v_mfma_f32_16x16x32_bf16 v[160:163], v[136:139], v[8:11], v[160:163]
	v_fma_f32 v220, v172, v179, -v180
	v_fma_f32 v221, v173, v179, -v180
	v_mfma_f32_16x16x32_bf16 v[164:167], v[136:139], v[40:43], v[164:167]
	v_fma_f32 v222, v174, v179, -v180
	v_fma_f32 v223, v175, v179, -v180
	v_mfma_f32_16x16x32_bf16 v[160:163], v[140:143], v[12:15], v[160:163]
	v_exp_f32_e32 v220, v220
	v_exp_f32_e32 v221, v221
	v_mfma_f32_16x16x32_bf16 v[164:167], v[140:143], v[44:47], v[164:167]
	v_exp_f32_e32 v222, v222
	v_exp_f32_e32 v223, v223
	v_mfma_f32_16x16x32_bf16 v[160:163], v[144:147], v[16:19], v[160:163]
	v_add_f32_e32 v176, v176, v216
	v_add_f32_e32 v176, v176, v217
	v_mfma_f32_16x16x32_bf16 v[164:167], v[144:147], v[48:51], v[164:167]
	v_cvt_pk_bf16_f32 v82, v216, v217
	v_add_f32_e32 v176, v176, v218
	v_mfma_f32_16x16x32_bf16 v[160:163], v[148:151], v[20:23], v[160:163]
	v_add_f32_e32 v176, v176, v219
	v_cvt_pk_bf16_f32 v83, v218, v219
	v_mfma_f32_16x16x32_bf16 v[164:167], v[148:151], v[52:55], v[164:167]
	v_add_f32_e32 v177, v177, v220
	v_add_f32_e32 v177, v177, v221
	v_mfma_f32_16x16x32_bf16 v[160:163], v[152:155], v[24:27], v[160:163]
	v_cvt_pk_bf16_f32 v114, v220, v221
	v_add_f32_e32 v177, v177, v222
	v_mfma_f32_16x16x32_bf16 v[164:167], v[152:155], v[56:59], v[164:167]
	v_add_f32_e32 v177, v177, v223
	v_cvt_pk_bf16_f32 v115, v222, v223
	v_mfma_f32_16x16x32_bf16 v[160:163], v[156:159], v[28:31], v[160:163]
	v_mfma_f32_16x16x32_bf16 v[164:167], v[156:159], v[60:63], v[164:167]
	s_waitcnt lgkmcnt(0)
	ds_read_b128 v[128:131], v233 offset:42240
	ds_read_b128 v[132:135], v233 offset:42304
	ds_read_b128 v[136:139], v233 offset:42368
	ds_read_b128 v[140:143], v233 offset:42432
	ds_read_b128 v[144:147], v233 offset:42496
	ds_read_b128 v[148:151], v233 offset:42560
	ds_read_b128 v[152:155], v233 offset:42624
	ds_read_b128 v[156:159], v233 offset:42688
	v_mfma_f32_16x16x32_bf16 v[168:171], v[184:187], v[0:3], 0
	v_fma_f32 v216, v160, v178, -v180
	v_fma_f32 v217, v161, v178, -v180
	v_mfma_f32_16x16x32_bf16 v[172:175], v[184:187], v[32:35], 0
	v_fma_f32 v218, v162, v178, -v180
	v_fma_f32 v219, v163, v178, -v180
	v_mfma_f32_16x16x32_bf16 v[168:171], v[188:191], v[4:7], v[168:171]
	v_exp_f32_e32 v216, v216
	v_exp_f32_e32 v217, v217
	v_mfma_f32_16x16x32_bf16 v[172:175], v[188:191], v[36:39], v[172:175]
	v_exp_f32_e32 v218, v218
	v_exp_f32_e32 v219, v219
	v_mfma_f32_16x16x32_bf16 v[168:171], v[192:195], v[8:11], v[168:171]
	v_fma_f32 v220, v164, v179, -v180
	v_fma_f32 v221, v165, v179, -v180
	v_mfma_f32_16x16x32_bf16 v[172:175], v[192:195], v[40:43], v[172:175]
	v_fma_f32 v222, v166, v179, -v180
	v_fma_f32 v223, v167, v179, -v180
	v_mfma_f32_16x16x32_bf16 v[168:171], v[196:199], v[12:15], v[168:171]
	v_exp_f32_e32 v220, v220
	v_exp_f32_e32 v221, v221
	v_mfma_f32_16x16x32_bf16 v[172:175], v[196:199], v[44:47], v[172:175]
	v_exp_f32_e32 v222, v222
	v_exp_f32_e32 v223, v223
	v_mfma_f32_16x16x32_bf16 v[168:171], v[200:203], v[16:19], v[168:171]
	v_add_f32_e32 v176, v176, v216
	v_add_f32_e32 v176, v176, v217
	v_mfma_f32_16x16x32_bf16 v[172:175], v[200:203], v[48:51], v[172:175]
	v_cvt_pk_bf16_f32 v84, v216, v217
	v_add_f32_e32 v176, v176, v218
	v_mfma_f32_16x16x32_bf16 v[168:171], v[204:207], v[20:23], v[168:171]
	v_add_f32_e32 v176, v176, v219
	v_cvt_pk_bf16_f32 v85, v218, v219
	v_mfma_f32_16x16x32_bf16 v[172:175], v[204:207], v[52:55], v[172:175]
	v_add_f32_e32 v177, v177, v220
	v_add_f32_e32 v177, v177, v221
	v_mfma_f32_16x16x32_bf16 v[168:171], v[208:211], v[24:27], v[168:171]
	v_cvt_pk_bf16_f32 v116, v220, v221
	v_add_f32_e32 v177, v177, v222
	v_mfma_f32_16x16x32_bf16 v[172:175], v[208:211], v[56:59], v[172:175]
	v_add_f32_e32 v177, v177, v223
	v_cvt_pk_bf16_f32 v117, v222, v223
	v_mfma_f32_16x16x32_bf16 v[168:171], v[212:215], v[28:31], v[168:171]
	v_mfma_f32_16x16x32_bf16 v[172:175], v[212:215], v[60:63], v[172:175]
	s_waitcnt lgkmcnt(0)
	ds_read_b128 v[184:187], v233 offset:50688
	ds_read_b128 v[188:191], v233 offset:50752
	ds_read_b128 v[192:195], v233 offset:50816
	ds_read_b128 v[196:199], v233 offset:50880
	ds_read_b128 v[200:203], v233 offset:50944
	ds_read_b128 v[204:207], v233 offset:51008
	ds_read_b128 v[208:211], v233 offset:51072
	ds_read_b128 v[212:215], v233 offset:51136
	v_mfma_f32_16x16x32_bf16 v[160:163], v[128:131], v[0:3], 0
	v_fma_f32 v216, v168, v178, -v180
	v_fma_f32 v217, v169, v178, -v180
	v_mfma_f32_16x16x32_bf16 v[164:167], v[128:131], v[32:35], 0
	v_fma_f32 v218, v170, v178, -v180
	v_fma_f32 v219, v171, v178, -v180
	v_mfma_f32_16x16x32_bf16 v[160:163], v[132:135], v[4:7], v[160:163]
	v_exp_f32_e32 v216, v216
	v_exp_f32_e32 v217, v217
	v_mfma_f32_16x16x32_bf16 v[164:167], v[132:135], v[36:39], v[164:167]
	v_exp_f32_e32 v218, v218
	v_exp_f32_e32 v219, v219
	v_mfma_f32_16x16x32_bf16 v[160:163], v[136:139], v[8:11], v[160:163]
	v_fma_f32 v220, v172, v179, -v180
	v_fma_f32 v221, v173, v179, -v180
	v_mfma_f32_16x16x32_bf16 v[164:167], v[136:139], v[40:43], v[164:167]
	v_fma_f32 v222, v174, v179, -v180
	v_fma_f32 v223, v175, v179, -v180
	v_mfma_f32_16x16x32_bf16 v[160:163], v[140:143], v[12:15], v[160:163]
	v_exp_f32_e32 v220, v220
	v_exp_f32_e32 v221, v221
	v_mfma_f32_16x16x32_bf16 v[164:167], v[140:143], v[44:47], v[164:167]
	v_exp_f32_e32 v222, v222
	v_exp_f32_e32 v223, v223
	v_mfma_f32_16x16x32_bf16 v[160:163], v[144:147], v[16:19], v[160:163]
	v_add_f32_e32 v176, v176, v216
	v_add_f32_e32 v176, v176, v217
	v_mfma_f32_16x16x32_bf16 v[164:167], v[144:147], v[48:51], v[164:167]
	v_cvt_pk_bf16_f32 v86, v216, v217
	v_add_f32_e32 v176, v176, v218
	v_mfma_f32_16x16x32_bf16 v[160:163], v[148:151], v[20:23], v[160:163]
	v_add_f32_e32 v176, v176, v219
	v_cvt_pk_bf16_f32 v87, v218, v219
	v_mfma_f32_16x16x32_bf16 v[164:167], v[148:151], v[52:55], v[164:167]
	v_add_f32_e32 v177, v177, v220
	v_add_f32_e32 v177, v177, v221
	v_mfma_f32_16x16x32_bf16 v[160:163], v[152:155], v[24:27], v[160:163]
	v_cvt_pk_bf16_f32 v118, v220, v221
	v_add_f32_e32 v177, v177, v222
	v_mfma_f32_16x16x32_bf16 v[164:167], v[152:155], v[56:59], v[164:167]
	v_add_f32_e32 v177, v177, v223
	v_cvt_pk_bf16_f32 v119, v222, v223
	v_mfma_f32_16x16x32_bf16 v[160:163], v[156:159], v[28:31], v[160:163]
	v_mfma_f32_16x16x32_bf16 v[164:167], v[156:159], v[60:63], v[164:167]
	s_waitcnt lgkmcnt(0)
	v_add_u32_e32 v233, 59136, v233
	ds_read_b128 v[128:131], v233 offset:0
	ds_read_b128 v[132:135], v233 offset:64
	ds_read_b128 v[136:139], v233 offset:128
	ds_read_b128 v[140:143], v233 offset:192
	ds_read_b128 v[144:147], v233 offset:256
	ds_read_b128 v[148:151], v233 offset:320
	ds_read_b128 v[152:155], v233 offset:384
	ds_read_b128 v[156:159], v233 offset:448
	v_mfma_f32_16x16x32_bf16 v[168:171], v[184:187], v[0:3], 0
	v_fma_f32 v216, v160, v178, -v180
	v_fma_f32 v217, v161, v178, -v180
	v_mfma_f32_16x16x32_bf16 v[172:175], v[184:187], v[32:35], 0
	v_fma_f32 v218, v162, v178, -v180
	v_fma_f32 v219, v163, v178, -v180
	v_mfma_f32_16x16x32_bf16 v[168:171], v[188:191], v[4:7], v[168:171]
	v_exp_f32_e32 v216, v216
	v_exp_f32_e32 v217, v217
	v_mfma_f32_16x16x32_bf16 v[172:175], v[188:191], v[36:39], v[172:175]
	v_exp_f32_e32 v218, v218
	v_exp_f32_e32 v219, v219
	v_mfma_f32_16x16x32_bf16 v[168:171], v[192:195], v[8:11], v[168:171]
	v_fma_f32 v220, v164, v179, -v180
	v_fma_f32 v221, v165, v179, -v180
	v_mfma_f32_16x16x32_bf16 v[172:175], v[192:195], v[40:43], v[172:175]
	v_fma_f32 v222, v166, v179, -v180
	v_fma_f32 v223, v167, v179, -v180
	v_mfma_f32_16x16x32_bf16 v[168:171], v[196:199], v[12:15], v[168:171]
	v_exp_f32_e32 v220, v220
	v_exp_f32_e32 v221, v221
	v_mfma_f32_16x16x32_bf16 v[172:175], v[196:199], v[44:47], v[172:175]
	v_exp_f32_e32 v222, v222
	v_exp_f32_e32 v223, v223
	v_mfma_f32_16x16x32_bf16 v[168:171], v[200:203], v[16:19], v[168:171]
	v_add_f32_e32 v176, v176, v216
	v_add_f32_e32 v176, v176, v217
	v_mfma_f32_16x16x32_bf16 v[172:175], v[200:203], v[48:51], v[172:175]
	v_cvt_pk_bf16_f32 v88, v216, v217
	v_add_f32_e32 v176, v176, v218
	v_mfma_f32_16x16x32_bf16 v[168:171], v[204:207], v[20:23], v[168:171]
	v_add_f32_e32 v176, v176, v219
	v_cvt_pk_bf16_f32 v89, v218, v219
	v_mfma_f32_16x16x32_bf16 v[172:175], v[204:207], v[52:55], v[172:175]
	v_add_f32_e32 v177, v177, v220
	v_add_f32_e32 v177, v177, v221
	v_mfma_f32_16x16x32_bf16 v[168:171], v[208:211], v[24:27], v[168:171]
	v_cvt_pk_bf16_f32 v120, v220, v221
	v_add_f32_e32 v177, v177, v222
	v_mfma_f32_16x16x32_bf16 v[172:175], v[208:211], v[56:59], v[172:175]
	v_add_f32_e32 v177, v177, v223
	v_cvt_pk_bf16_f32 v121, v222, v223
	v_mfma_f32_16x16x32_bf16 v[168:171], v[212:215], v[28:31], v[168:171]
	v_mfma_f32_16x16x32_bf16 v[172:175], v[212:215], v[60:63], v[172:175]
	s_waitcnt lgkmcnt(0)
	ds_read_b128 v[184:187], v233 offset:8448
	ds_read_b128 v[188:191], v233 offset:8512
	ds_read_b128 v[192:195], v233 offset:8576
	ds_read_b128 v[196:199], v233 offset:8640
	ds_read_b128 v[200:203], v233 offset:8704
	ds_read_b128 v[204:207], v233 offset:8768
	ds_read_b128 v[208:211], v233 offset:8832
	ds_read_b128 v[212:215], v233 offset:8896
	v_mfma_f32_16x16x32_bf16 v[160:163], v[128:131], v[0:3], 0
	v_fma_f32 v216, v168, v178, -v180
	v_fma_f32 v217, v169, v178, -v180
	v_mfma_f32_16x16x32_bf16 v[164:167], v[128:131], v[32:35], 0
	v_fma_f32 v218, v170, v178, -v180
	v_fma_f32 v219, v171, v178, -v180
	v_mfma_f32_16x16x32_bf16 v[160:163], v[132:135], v[4:7], v[160:163]
	v_exp_f32_e32 v216, v216
	v_exp_f32_e32 v217, v217
	v_mfma_f32_16x16x32_bf16 v[164:167], v[132:135], v[36:39], v[164:167]
	v_exp_f32_e32 v218, v218
	v_exp_f32_e32 v219, v219
	v_mfma_f32_16x16x32_bf16 v[160:163], v[136:139], v[8:11], v[160:163]
	v_fma_f32 v220, v172, v179, -v180
	v_fma_f32 v221, v173, v179, -v180
	v_mfma_f32_16x16x32_bf16 v[164:167], v[136:139], v[40:43], v[164:167]
	v_fma_f32 v222, v174, v179, -v180
	v_fma_f32 v223, v175, v179, -v180
	v_mfma_f32_16x16x32_bf16 v[160:163], v[140:143], v[12:15], v[160:163]
	v_exp_f32_e32 v220, v220
	v_exp_f32_e32 v221, v221
	v_mfma_f32_16x16x32_bf16 v[164:167], v[140:143], v[44:47], v[164:167]
	v_exp_f32_e32 v222, v222
	v_exp_f32_e32 v223, v223
	v_mfma_f32_16x16x32_bf16 v[160:163], v[144:147], v[16:19], v[160:163]
	v_add_f32_e32 v176, v176, v216
	v_add_f32_e32 v176, v176, v217
	v_mfma_f32_16x16x32_bf16 v[164:167], v[144:147], v[48:51], v[164:167]
	v_cvt_pk_bf16_f32 v90, v216, v217
	v_add_f32_e32 v176, v176, v218
	v_mfma_f32_16x16x32_bf16 v[160:163], v[148:151], v[20:23], v[160:163]
	v_add_f32_e32 v176, v176, v219
	v_cvt_pk_bf16_f32 v91, v218, v219
	v_mfma_f32_16x16x32_bf16 v[164:167], v[148:151], v[52:55], v[164:167]
	v_add_f32_e32 v177, v177, v220
	v_add_f32_e32 v177, v177, v221
	v_mfma_f32_16x16x32_bf16 v[160:163], v[152:155], v[24:27], v[160:163]
	v_cvt_pk_bf16_f32 v122, v220, v221
	v_add_f32_e32 v177, v177, v222
	v_mfma_f32_16x16x32_bf16 v[164:167], v[152:155], v[56:59], v[164:167]
	v_add_f32_e32 v177, v177, v223
	v_cvt_pk_bf16_f32 v123, v222, v223
	v_mfma_f32_16x16x32_bf16 v[160:163], v[156:159], v[28:31], v[160:163]
	v_mfma_f32_16x16x32_bf16 v[164:167], v[156:159], v[60:63], v[164:167]
	s_waitcnt lgkmcnt(0)
	s_nop 6
	v_mfma_f32_16x16x32_bf16 v[168:171], v[184:187], v[0:3], 0
	v_fma_f32 v216, v160, v178, -v180
	v_fma_f32 v217, v161, v178, -v180
	v_mfma_f32_16x16x32_bf16 v[172:175], v[184:187], v[32:35], 0
	v_fma_f32 v218, v162, v178, -v180
	v_fma_f32 v219, v163, v178, -v180
	v_mfma_f32_16x16x32_bf16 v[168:171], v[188:191], v[4:7], v[168:171]
	v_exp_f32_e32 v216, v216
	v_exp_f32_e32 v217, v217
	v_mfma_f32_16x16x32_bf16 v[172:175], v[188:191], v[36:39], v[172:175]
	v_exp_f32_e32 v218, v218
	v_exp_f32_e32 v219, v219
	v_mfma_f32_16x16x32_bf16 v[168:171], v[192:195], v[8:11], v[168:171]
	v_fma_f32 v220, v164, v179, -v180
	v_fma_f32 v221, v165, v179, -v180
	v_mfma_f32_16x16x32_bf16 v[172:175], v[192:195], v[40:43], v[172:175]
	v_fma_f32 v222, v166, v179, -v180
	v_fma_f32 v223, v167, v179, -v180
	v_mfma_f32_16x16x32_bf16 v[168:171], v[196:199], v[12:15], v[168:171]
	v_exp_f32_e32 v220, v220
	v_exp_f32_e32 v221, v221
	v_mfma_f32_16x16x32_bf16 v[172:175], v[196:199], v[44:47], v[172:175]
	v_exp_f32_e32 v222, v222
	v_exp_f32_e32 v223, v223
	v_mfma_f32_16x16x32_bf16 v[168:171], v[200:203], v[16:19], v[168:171]
	v_add_f32_e32 v176, v176, v216
	v_add_f32_e32 v176, v176, v217
	v_mfma_f32_16x16x32_bf16 v[172:175], v[200:203], v[48:51], v[172:175]
	v_cvt_pk_bf16_f32 v92, v216, v217
	v_add_f32_e32 v176, v176, v218
	v_mfma_f32_16x16x32_bf16 v[168:171], v[204:207], v[20:23], v[168:171]
	v_add_f32_e32 v176, v176, v219
	v_cvt_pk_bf16_f32 v93, v218, v219
	v_mfma_f32_16x16x32_bf16 v[172:175], v[204:207], v[52:55], v[172:175]
	v_add_f32_e32 v177, v177, v220
	v_add_f32_e32 v177, v177, v221
	v_mfma_f32_16x16x32_bf16 v[168:171], v[208:211], v[24:27], v[168:171]
	v_cvt_pk_bf16_f32 v124, v220, v221
	v_add_f32_e32 v177, v177, v222
	v_mfma_f32_16x16x32_bf16 v[172:175], v[208:211], v[56:59], v[172:175]
	v_add_f32_e32 v177, v177, v223
	v_cvt_pk_bf16_f32 v125, v222, v223
	v_mfma_f32_16x16x32_bf16 v[168:171], v[212:215], v[28:31], v[168:171]
	v_mfma_f32_16x16x32_bf16 v[172:175], v[212:215], v[60:63], v[172:175]
	s_nop 7
	v_fma_f32 v216, v168, v178, -v180
	v_fma_f32 v217, v169, v178, -v180
	v_fma_f32 v218, v170, v178, -v180
	v_fma_f32 v219, v171, v178, -v180
	v_exp_f32_e32 v216, v216
	v_exp_f32_e32 v217, v217
	v_exp_f32_e32 v218, v218
	v_exp_f32_e32 v219, v219
	v_fma_f32 v220, v172, v179, -v180
	v_fma_f32 v221, v173, v179, -v180
	v_fma_f32 v222, v174, v179, -v180
	v_fma_f32 v223, v175, v179, -v180
	v_exp_f32_e32 v220, v220
	v_exp_f32_e32 v221, v221
	v_exp_f32_e32 v222, v222
	v_exp_f32_e32 v223, v223
	v_add_f32_e32 v176, v176, v216
	v_add_f32_e32 v176, v176, v217
	v_cvt_pk_bf16_f32 v94, v216, v217
	v_add_f32_e32 v176, v176, v218
	v_add_f32_e32 v176, v176, v219
	v_cvt_pk_bf16_f32 v95, v218, v219
	v_add_f32_e32 v177, v177, v220
	v_add_f32_e32 v177, v177, v221
	v_cvt_pk_bf16_f32 v126, v220, v221
	v_add_f32_e32 v177, v177, v222
	v_add_f32_e32 v177, v177, v223
	v_cvt_pk_bf16_f32 v127, v222, v223
	s_barrier
	global_load_dwordx4 v[128:131], v225, s[8:9]
	s_add_u32 s8, s8, 0x14000
	s_addc_u32 s9, s9, 0
	global_load_dwordx4 v[132:135], v225, s[8:9]
	s_add_u32 s8, s8, 0x14000
	s_addc_u32 s9, s9, 0
	global_load_dwordx4 v[136:139], v225, s[8:9]
	s_add_u32 s8, s8, 0x14000
	s_addc_u32 s9, s9, 0
	global_load_dwordx4 v[140:143], v225, s[8:9]
	s_add_u32 s8, s8, 0x14000
	s_addc_u32 s9, s9, 0
	global_load_dwordx4 v[144:147], v225, s[8:9]
	s_add_u32 s8, s8, 0x14000
	s_addc_u32 s9, s9, 0
	global_load_dwordx4 v[148:151], v225, s[8:9]
	s_add_u32 s8, s8, 0x14000
	s_addc_u32 s9, s9, 0
	global_load_dwordx4 v[152:155], v225, s[8:9]
	s_add_u32 s8, s8, 0x14000
	s_addc_u32 s9, s9, 0
	global_load_dwordx4 v[156:159], v225, s[8:9]
	s_add_u32 s8, s8, 0x14000
	s_addc_u32 s9, s9, 0
	global_load_dwordx4 v[184:187], v225, s[8:9]
	s_add_u32 s8, s8, 0x14000
	s_addc_u32 s9, s9, 0
	global_load_dwordx4 v[188:191], v225, s[8:9]
	s_add_u32 s8, s8, 0x14000
	s_addc_u32 s9, s9, 0
	global_load_dwordx4 v[192:195], v225, s[8:9]
	s_add_u32 s8, s8, 0x14000
	s_addc_u32 s9, s9, 0
	global_load_dwordx4 v[196:199], v225, s[8:9]
	s_add_u32 s8, s8, 0x14000
	s_addc_u32 s9, s9, 0
	global_load_dwordx4 v[200:203], v225, s[8:9]
	s_add_u32 s8, s8, 0x14000
	s_addc_u32 s9, s9, 0
	global_load_dwordx4 v[204:207], v225, s[8:9]
	s_add_u32 s8, s8, 0x14000
	s_addc_u32 s9, s9, 0
	global_load_dwordx4 v[208:211], v225, s[8:9]
	s_add_u32 s8, s8, 0x14000
	s_addc_u32 s9, s9, 0
	global_load_dwordx4 v[212:215], v225, s[8:9]
	s_add_i32 s16, s69, s86
	s_cmpk_lt_i32 s16, 0x300
	s_cselect_b32 s16, s16, s69
	s_and_b32 s0, s16, 31
	s_lshr_b32 s1, s16, 8
	s_lshl_b32 s1, s1, 5
	s_add_i32 s1, s1, s0
	s_mul_i32 s0, s1, 2731
	s_lshr_b32 s0, s0, 16
	s_mul_i32 s17, s0, 24
	s_sub_i32 s1, s1, s17
	s_bfe_u32 s17, s16, 0x30005
	s_mul_i32 s17, s17, 24
	s_add_i32 s1, s1, s17
	s_lshl_b32 s11, s1, 19
	s_lshl_b32 s12, s0, 9
	s_add_u32 s11, s11, s12
	s_add_u32 s12, s11, 0xf000000
	s_add_u32 s10, s4, s12
	s_addc_u32 s11, s5, 0
	s_lshl_b32 s12, s1, 12
	s_lshl_b32 s13, s0, 2
	s_add_u32 s12, s12, s13
	s_add_u32 s12, s12, 0x1fa60000
	s_add_u32 s12, s4, s12
	s_addc_u32 s13, s5, 0
	global_load_dwordx4 v[0:3], v228, s[10:11] offset:0
	global_load_dwordx4 v[4:7], v228, s[10:11] offset:64
	global_load_dwordx4 v[8:11], v228, s[10:11] offset:128
	global_load_dwordx4 v[12:15], v228, s[10:11] offset:192
	global_load_dwordx4 v[16:19], v228, s[10:11] offset:256
	global_load_dwordx4 v[20:23], v228, s[10:11] offset:320
	global_load_dwordx4 v[24:27], v228, s[10:11] offset:384
	global_load_dwordx4 v[28:31], v228, s[10:11] offset:448
	global_load_dwordx4 v[32:35], v229, s[10:11] offset:0
	global_load_dwordx4 v[36:39], v229, s[10:11] offset:64
	global_load_dwordx4 v[40:43], v229, s[10:11] offset:128
	global_load_dwordx4 v[44:47], v229, s[10:11] offset:192
	global_load_dwordx4 v[48:51], v229, s[10:11] offset:256
	global_load_dwordx4 v[52:55], v229, s[10:11] offset:320
	global_load_dwordx4 v[56:59], v229, s[10:11] offset:384
	global_load_dwordx4 v[60:63], v229, s[10:11] offset:448
	global_load_dword v247, v230, s[12:13]
	global_load_dword v248, v230, s[12:13] offset:2048
	ds_bpermute_b32 v242, v236, v176
	s_waitcnt lgkmcnt(0)
	v_add_f32_e32 v176, v176, v242
	ds_bpermute_b32 v242, v237, v176
	s_waitcnt lgkmcnt(0)
	v_add_f32_e32 v176, v176, v242
	ds_bpermute_b32 v242, v236, v177
	s_waitcnt lgkmcnt(0)
	v_add_f32_e32 v177, v177, v242
	ds_bpermute_b32 v242, v237, v177
	s_waitcnt lgkmcnt(0)
	v_add_f32_e32 v177, v177, v242
	v_rcp_f32_e32 v240, v176
	v_rcp_f32_e32 v241, v177
	s_waitcnt vmcnt(30)
	ds_write_b128 v250, v[128:131] offset:0
	ds_write_b128 v250, v[132:135] offset:4224
	ds_write_b128 v250, v[136:139] offset:16896
	ds_write_b128 v250, v[140:143] offset:21120
	s_waitcnt vmcnt(26)
	ds_write_b128 v250, v[144:147] offset:33792
	ds_write_b128 v250, v[148:151] offset:38016
	ds_write_b128 v250, v[152:155] offset:50688
	ds_write_b128 v250, v[156:159] offset:54912
	s_waitcnt vmcnt(22)
	ds_write_b128 v251, v[184:187] offset:0
	ds_write_b128 v251, v[188:191] offset:4224
	ds_write_b128 v251, v[192:195] offset:16896
	ds_write_b128 v251, v[196:199] offset:21120
	s_waitcnt vmcnt(18)
	ds_write_b128 v251, v[200:203] offset:33792
	ds_write_b128 v251, v[204:207] offset:38016
	ds_write_b128 v251, v[208:211] offset:50688
	ds_write_b128 v251, v[212:215] offset:54912
	s_waitcnt lgkmcnt(0)
	s_barrier
	s_mov_b32 s18, 0
	v_mov_b32_e32 v234, v232
	v_add_u32_e32 v235, 16896, v232
	ds_read_b64 v[128:129], v234 offset:0
	ds_read_b64 v[130:131], v234 offset:32
	ds_read_b64 v[132:133], v234 offset:64
	ds_read_b64 v[134:135], v234 offset:96
	ds_read_b64 v[136:137], v234 offset:128
	ds_read_b64 v[138:139], v234 offset:160
	ds_read_b64 v[140:141], v234 offset:192
	ds_read_b64 v[142:143], v234 offset:224
	ds_read_b64 v[144:145], v234 offset:256
	ds_read_b64 v[146:147], v234 offset:288
	ds_read_b64 v[148:149], v234 offset:320
	ds_read_b64 v[150:151], v234 offset:352
